# attention: first and last (peeled) key steps get the same batched K/V LDS reads as the main loop
# speedup vs baseline: 1.0154x; 1.0063x over previous
; __device__ __forceinline__ void ph_attn(KP p, int l, unsigned char* sm, int wv) {
;     ...
;             for (int s = 0; s < 9; ++s) {
;                 const int kk0 = 16 * wid + 32 * s;
;                 f32x4 st[2];
; #pragma unroll
;                 for (int kt = 0; kt < 2; ++kt) {
;                     st[kt] = (f32x4){0.f, 0.f, 0.f, 0.f};
; #pragma unroll
;                     for (int ks = 0; ks < 2; ++ks) {
;                         const bf16x8 kf = *(const bf16x8*)(Ks + (kk0 + 16 * kt + fr) * 72 + 32 * ks + 8 * fq);
;                         st[kt] = __builtin_amdgcn_mfma_f32_16x16x32_bf16(kf, qf[ks], st[kt], 0, 0, 0);
;                     }
;                 }
;                 float sv[2][4]; float mx = -1e30f;
;                 if (interior && s >= 1 && s <= 7) {
; #pragma unroll
;                     for (int kt = 0; kt < 2; ++kt)
; #pragma unroll
;                         for (int r = 0; r < 4; ++r) { sv[kt][r] = st[kt][r]; mx = fmaxf(mx, sv[kt][r]); }
;                 } else {
; #pragma unroll
;                     for (int kt = 0; kt < 2; ++kt)
; #pragma unroll
;                         for (int r = 0; r < 4; ++r) {
;                             const int kk = kk0 + 16 * kt + 4 * fq + r, d = kk - 128 - qi, prel = Q0rel + kk - 128;
;                             const bool valid = d >= -128 && d <= 128 && prel >= 0 && prel < L && kk < 384;
;                             sv[kt][r] = valid ? st[kt][r] : -1e30f;
;                             mx = fmaxf(mx, sv[kt][r]);
;                         }
;                 }
;                 mx = fmaxf(mx, shx(mx, 16, lane)); mx = fmaxf(mx, shx(mx, 32, lane));
;                 const float mn = fmaxf(mrun, mx), alpha = __builtin_amdgcn_exp2f(mrun - mn);
;                 mrun = mn;
;                 float pr[2][4], psum = 0.f;
; #pragma unroll
;                 for (int kt = 0; kt < 2; ++kt)
; #pragma unroll
;                     for (int r = 0; r < 4; ++r) { pr[kt][r] = __builtin_amdgcn_exp2f(sv[kt][r] - mn); psum += pr[kt][r]; }
;                 lsum = lsum * alpha + psum;
;                 const bool rescale = __builtin_amdgcn_ballot_w64(alpha != 1.0f) != 0ull;
;                 union { bf16x8 v; unsigned u[4]; } pf;
;                 pf.u[0] = pk2(pr[0][0], pr[0][1]); pf.u[1] = pk2(pr[0][2], pr[0][3]); pf.u[2] = pk2(pr[1][0], pr[1][1]); pf.u[3] = pk2(pr[1][2], pr[1][3]);
; #pragma unroll
.LBB0_837:
	ds_read_b128 v[160:163], v157
	ds_read_b128 v[164:167], v157 offset:64
	ds_read_b128 v[224:227], v157 offset:2304
	ds_read_b128 v[182:185], v157 offset:2368
	ds_read2_b64 v[186:189], v159 offset0:96 offset1:100
	ds_read2_b64 v[190:193], v141 offset1:4
	ds_read2_b64 v[194:197], v142 offset1:4
	ds_read2_b64 v[198:201], v143 offset1:4
	s_waitcnt lgkmcnt(7)
	v_mfma_f32_16x16x32_bf16 v[160:163], v[160:163], v[38:41], 0
	s_waitcnt lgkmcnt(6)
	v_mfma_f32_16x16x32_bf16 v[160:163], v[164:167], v[34:37], v[160:163]
	s_waitcnt lgkmcnt(5)
	v_mfma_f32_16x16x32_bf16 v[38:41], v[224:227], v[38:41], 0
	s_nop 5
	v_cndmask_b32_e64 v59, v243, v163, s[78:79]
	s_waitcnt lgkmcnt(4)
	v_mfma_f32_16x16x32_bf16 v[34:37], v[182:185], v[34:37], v[38:41]
	s_nop 2
	v_cndmask_b32_e64 v38, v243, v160, s[72:73]
	v_cndmask_b32_e64 v39, v243, v161, s[74:75]
	v_max3_f32 v40, v38, s35, v39
	v_cndmask_b32_e64 v41, v243, v162, s[76:77]
	v_max3_f32 v40, v40, v41, v59
	v_cndmask_b32_e64 v34, v243, v34, s[80:81]
	v_cndmask_b32_e64 v35, v243, v35, s[82:83]
	v_max3_f32 v40, v40, v34, v35
	v_cndmask_b32_e64 v36, v243, v36, s[84:85]
	v_cndmask_b32_e64 v37, v243, v37, s[86:87]
	v_max3_f32 v40, v40, v36, v37
	ds_bpermute_b32 v60, v103, v40
	s_waitcnt lgkmcnt(0)
	v_max_f32_e32 v60, v60, v60
	v_max_f32_e32 v40, v40, v60
	ds_bpermute_b32 v60, v104, v40
	s_waitcnt lgkmcnt(0)
	v_max3_f32 v40, v63, v40, v60
	v_sub_f32_e32 v38, v38, v40
	v_exp_f32_e32 v61, v38
	v_sub_f32_e32 v39, v39, v40
	v_exp_f32_e32 v39, v39
	v_sub_f32_e32 v41, v41, v40
	v_exp_f32_e32 v41, v41
	v_sub_f32_e32 v59, v59, v40
	v_exp_f32_e32 v59, v59
	v_add_f32_e32 v38, 0, v61
	v_add_f32_e32 v38, v39, v38
	v_sub_f32_e32 v60, v63, v40
	v_add_f32_e32 v38, v41, v38
	v_add_f32_e32 v64, v59, v38
	v_exp_f32_e32 v38, v60
	v_sub_f32_e32 v34, v34, v40
	v_exp_f32_e32 v65, v34
	v_sub_f32_e32 v34, v35, v40
	v_exp_f32_e32 v160, v34
	v_sub_f32_e32 v34, v36, v40
	v_cmp_neq_f32_e32 vcc, 1.0, v38
	v_exp_f32_e32 v161, v34
	v_sub_f32_e32 v34, v37, v40
	s_cmp_eq_u64 vcc, 0
	v_exp_f32_e32 v162, v34
	s_cselect_b64 vcc, -1, 0
	v_pk_mul_f32 v[34:35], v[46:47], v[38:39] op_sel_hi:[1,0]
	v_pk_mul_f32 v[36:37], v[48:49], v[38:39] op_sel_hi:[1,0]
	v_cvt_pk_bf16_f32 v60, v61, v39
	v_cvt_pk_bf16_f32 v61, v41, v59
	v_cvt_pk_bf16_f32 v62, v65, v160
	v_cvt_pk_bf16_f32 v63, v161, v162
	v_cndmask_b32_e32 v35, v35, v47, vcc
	v_cndmask_b32_e32 v37, v37, v49, vcc
	v_cndmask_b32_e32 v36, v36, v48, vcc
	v_cndmask_b32_e32 v34, v34, v46, vcc
	v_pk_mul_f32 v[40:41], v[38:39], v[52:53] op_sel_hi:[0,1]
	s_waitcnt lgkmcnt(0)
	v_mfma_f32_16x16x32_bf16 v[34:37], v[186:189], v[60:63], v[34:37]
	v_mul_f32_e64 v46, v38, v50
	v_mul_f32_e64 v47, v38, v51
	v_cndmask_b32_e32 v49, v41, v53, vcc
	v_cndmask_b32_e32 v48, v40, v52, vcc
	v_cndmask_b32_e32 v47, v47, v51, vcc
	v_cndmask_b32_e32 v46, v46, v50, vcc
	v_pk_mul_f32 v[40:41], v[38:39], v[44:45] op_sel_hi:[0,1]
	s_nop 0
	v_mfma_f32_16x16x32_bf16 v[46:49], v[190:193], v[60:63], v[46:49]
	v_mul_f32_e64 v50, v38, v42
	v_mul_f32_e64 v51, v38, v43
	v_cndmask_b32_e32 v43, v51, v43, vcc
	v_cndmask_b32_e32 v42, v50, v42, vcc
	v_cndmask_b32_e32 v45, v41, v45, vcc
	v_cndmask_b32_e32 v44, v40, v44, vcc
	s_add_i32 s39, s39, 1
	s_nop 0
	v_mfma_f32_16x16x32_bf16 v[40:43], v[194:197], v[60:63], v[42:45]
	s_nop 2
	v_mul_f32_e64 v44, v38, v56
	v_mul_f32_e64 v45, v38, v57
	v_pk_mul_f32 v[50:51], v[38:39], v[54:55] op_sel_hi:[0,1]
	v_add_f32_e32 v39, v65, v64
	v_add_f32_e32 v39, v160, v39
	v_add_f32_e32 v39, v161, v39
	v_add_f32_e32 v39, v162, v39
	v_fmac_f32_e32 v39, v58, v38
	ds_bpermute_b32 v38, v103, v39
	v_cndmask_b32_e32 v53, v45, v57, vcc
	v_cndmask_b32_e32 v52, v44, v56, vcc
	v_cndmask_b32_e32 v51, v51, v55, vcc
	v_cndmask_b32_e32 v50, v50, v54, vcc
	s_waitcnt lgkmcnt(0)
	v_add_f32_e32 v38, v39, v38
	ds_bpermute_b32 v39, v104, v38
	s_waitcnt lgkmcnt(0)
	v_mfma_f32_16x16x32_bf16 v[50:53], v[198:201], v[60:63], v[50:53]
	v_add_f32_e32 v38, v38, v39
	v_div_scale_f32 v39, s[2:3], v38, v38, 1.0
	v_rcp_f32_e32 v44, v39
	v_readlane_b32 s2, v254, 22
	v_readlane_b32 s3, v254, 23
	s_load_dwordx2 s[2:3], s[2:3], 0xf8
	v_fma_f32 v45, -v39, v44, 1.0
	v_fmac_f32_e32 v44, v45, v44
	v_div_scale_f32 v45, vcc, 1.0, v38, 1.0
	v_mul_f32_e32 v54, v45, v44
	v_fma_f32 v55, -v39, v54, v45
	v_fmac_f32_e32 v54, v55, v44
	v_fma_f32 v39, -v39, v54, v45
	v_div_fmas_f32 v39, v39, v44, v54
	v_div_fixup_f32 v44, v39, v38, 1.0
	s_waitcnt lgkmcnt(0)
	v_lshl_add_u64 v[38:39], s[2:3], 0, v[92:93]
	s_lshl_b32 s2, s40, 6
	s_ashr_i32 s3, s2, 31
	v_mul_f32_e32 v34, v44, v34
	v_mul_f32_e32 v35, v44, v35
	v_lshl_add_u64 v[38:39], s[2:3], 1, v[38:39]
	v_cvt_pk_bf16_f32 v34, v34, v35
	v_mul_f32_e32 v35, v44, v36
	v_lshl_add_u64 v[38:39], v[38:39], 0, v[0:1]
	v_mul_f32_e32 v36, v44, v37
	v_cvt_pk_bf16_f32 v35, v35, v36
	global_store_dwordx2 v[38:39], v[34:35], off
	v_mul_f32_e32 v34, v44, v46
	v_mul_f32_e32 v35, v44, v47
	v_cvt_pk_bf16_f32 v34, v34, v35
	v_mul_f32_e32 v35, v44, v48
	v_mul_f32_e32 v36, v44, v49
	v_cvt_pk_bf16_f32 v35, v35, v36
	global_store_dwordx2 v[38:39], v[34:35], off offset:32
	v_mul_f32_e32 v34, v44, v40
	v_mul_f32_e32 v35, v44, v41
	v_cvt_pk_bf16_f32 v34, v34, v35
	v_mul_f32_e32 v35, v44, v42
	v_mul_f32_e32 v36, v44, v43
	v_cvt_pk_bf16_f32 v35, v35, v36
	global_store_dwordx2 v[38:39], v[34:35], off offset:64
	v_mul_f32_e32 v34, v50, v44
	v_mul_f32_e32 v35, v51, v44
	v_cvt_pk_bf16_f32 v34, v34, v35
	v_mul_f32_e32 v35, v52, v44
	s_cmp_eq_u32 s39, 4
	v_mul_f32_e32 v36, v53, v44
	v_cvt_pk_bf16_f32 v35, v35, v36
	global_store_dwordx2 v[38:39], v[34:35], off offset:96
	s_cbranch_scc1 .LBB0_809

; __device__ __forceinline__ void ph_attn(KP p, int l, unsigned char* sm, int wv) {
;     ...
;                 qk_prep_store(qsa, qsb, qg, sub, Q0rel + row, 0.125f * 1.4426950408889634f, Qs + row * 72 + sub * 16, lane);
;             }
;             __syncthreads();
;             bf16x8 qf[2];
; #pragma unroll
;             for (int ks = 0; ks < 2; ++ks) qf[ks] = *(const bf16x8*)(Qs + (16 * wid + fr) * 72 + 32 * ks + 8 * fq);
;             f32x4 o[4];
; #pragma unroll
;             for (int dt = 0; dt < 4; ++dt) o[dt] = (f32x4){0.f, 0.f, 0.f, 0.f};
;             float mrun = p->sink[l * 8 + h] * 1.4426950408889634f;
;             float lsum = fq == 0 ? 1.0f : 0.0f;
;             const int qi = 16 * wid + fr;
;             for (int s = 0; s < 9; ++s) {
;                 const int kk0 = 16 * wid + 32 * s;
;                 f32x4 st[2];
; #pragma unroll
;                 for (int kt = 0; kt < 2; ++kt) {
;                     st[kt] = (f32x4){0.f, 0.f, 0.f, 0.f};
; #pragma unroll
;                     for (int ks = 0; ks < 2; ++ks) {
;                         const bf16x8 kf = *(const bf16x8*)(Ks + (kk0 + 16 * kt + fr) * 72 + 32 * ks + 8 * fq);
;                         st[kt] = __builtin_amdgcn_mfma_f32_16x16x32_bf16(kf, qf[ks], st[kt], 0, 0, 0);
;                     }
;                 }
;                 float sv[2][4]; float mx = -1e30f;
;                 if (interior && s >= 1 && s <= 7) {
; #pragma unroll
;                     for (int kt = 0; kt < 2; ++kt)
; #pragma unroll
;                         for (int r = 0; r < 4; ++r) { sv[kt][r] = st[kt][r]; mx = fmaxf(mx, sv[kt][r]); }
;                 } else {
; #pragma unroll
;                     for (int kt = 0; kt < 2; ++kt)
; #pragma unroll
;                         for (int r = 0; r < 4; ++r) {
;                             const int kk = kk0 + 16 * kt + 4 * fq + r, d = kk - 128 - qi, prel = Q0rel + kk - 128;
;                             const bool valid = d >= -128 && d <= 128 && prel >= 0 && prel < L && kk < 384;
;                             sv[kt][r] = valid ? st[kt][r] : -1e30f;
;                             mx = fmaxf(mx, sv[kt][r]);
;                         }
;                 }
;                 mx = fmaxf(mx, shx(mx, 16, lane)); mx = fmaxf(mx, shx(mx, 32, lane));
;                 const float mn = fmaxf(mrun, mx), alpha = __builtin_amdgcn_exp2f(mrun - mn);
;                 mrun = mn;
.LBB0_846:
	s_or_b64 exec, exec, s[2:3]
	v_mul_f32_e32 v41, 0x3e38aa3b, v50
	v_mul_f32_e32 v43, 0x3e38aa3b, v51
	v_cvt_pk_bf16_f32 v50, v41, v43
	v_mul_f32_e32 v41, 0x3e38aa3b, v48
	v_mul_f32_e32 v43, 0x3e38aa3b, v49
	v_cvt_pk_bf16_f32 v51, v41, v43
	v_mul_f32_e32 v41, 0x3e38aa3b, v46
	v_mul_f32_e32 v34, 0x3e38aa3b, v34
	v_mul_f32_e32 v35, 0x3e38aa3b, v35
	v_readlane_b32 s2, v254, 22
	v_mul_f32_e32 v43, 0x3e38aa3b, v47
	v_cvt_pk_bf16_f32 v52, v41, v43
	v_mul_f32_e32 v41, 0x3e38aa3b, v42
	v_mul_f32_e32 v42, 0x3e38aa3b, v45
	v_cvt_pk_bf16_f32 v53, v41, v42
	v_mul_f32_e32 v38, 0x3e38aa3b, v38
	v_mul_f32_e32 v39, 0x3e38aa3b, v39
	v_cvt_pk_bf16_f32 v46, v38, v39
	v_mul_f32_e32 v36, 0x3e38aa3b, v36
	v_mul_f32_e32 v37, 0x3e38aa3b, v37
	v_cvt_pk_bf16_f32 v47, v36, v37
	v_cvt_pk_bf16_f32 v48, v34, v35
	v_mul_f32_e32 v34, 0x3e38aa3b, v40
	v_mul_f32_e32 v35, 0x3e38aa3b, v44
	v_readlane_b32 s3, v254, 23
	v_cvt_pk_bf16_f32 v49, v34, v35
	ds_write_b128 v98, v[50:53]
	ds_write_b128 v98, v[46:49] offset:16
	s_waitcnt lgkmcnt(0)
	s_barrier
	ds_read_b128 v[38:41], v156
	ds_read_b128 v[34:37], v156 offset:64
	s_load_dwordx2 s[2:3], s[2:3], 0x40
	s_add_i32 s40, s39, s38
	s_add_i32 s18, s40, s31
	s_ashr_i32 s19, s18, 31
	s_lshl_b64 s[18:19], s[18:19], 2
	s_waitcnt lgkmcnt(0)
	s_add_u32 s2, s2, s18
	s_addc_u32 s3, s3, s19
	global_load_dword v54, v1, s[2:3]
	v_add_u32_e32 v50, v102, v100
	ds_read_b128 v[42:45], v50
	ds_read_b128 v[46:49], v50 offset:64
	ds_read_b128 v[224:227], v50 offset:2304
	ds_read_b128 v[182:185], v50 offset:2368
	s_waitcnt lgkmcnt(3)
	v_mfma_f32_16x16x32_bf16 v[42:45], v[42:45], v[38:41], 0
	s_mov_b32 s2, 0x3fb8aa3b
	v_add_u32_e32 v159, 0xe000, v140
	s_mov_b32 s42, 0
	s_waitcnt lgkmcnt(2)
	v_mfma_f32_16x16x32_bf16 v[42:45], v[46:49], v[34:37], v[42:45]
	ds_read2_b64 v[186:189], v159 offset0:32 offset1:36
	ds_read2_b64 v[198:201], v150 offset1:4
	ds_read2_b64 v[190:193], v148 offset1:4
	ds_read2_b64 v[194:197], v149 offset1:4
	s_waitcnt vmcnt(0)
	v_mul_f32_e32 v55, 0x3fb8aa3b, v54
	s_waitcnt lgkmcnt(5)
	v_mfma_f32_16x16x32_bf16 v[46:49], v[224:227], v[38:41], 0
	s_nop 1
	v_cndmask_b32_e64 v42, v243, v42, s[88:89]
	v_cndmask_b32_e64 v43, v243, v43, s[90:91]
	v_cndmask_b32_e64 v44, v243, v44, s[92:93]
	s_waitcnt lgkmcnt(4)
	v_mfma_f32_16x16x32_bf16 v[46:49], v[182:185], v[34:37], v[46:49]
	v_max3_f32 v50, v42, s35, v43
	v_cndmask_b32_e64 v45, v243, v45, s[94:95]
	v_max3_f32 v50, v50, v44, v45
	s_nop 4
	v_cndmask_b32_e64 v46, v243, v46, s[96:97]
	v_cndmask_b32_e64 v47, v243, v47, s[16:17]
	v_max3_f32 v50, v50, v46, v47
	v_cndmask_b32_e64 v48, v243, v48, s[14:15]
	v_cndmask_b32_e64 v49, v243, v49, s[0:1]
	v_max3_f32 v50, v50, v48, v49
	ds_bpermute_b32 v51, v103, v50
	s_waitcnt lgkmcnt(0)
	v_max_f32_e32 v51, v51, v51
	v_max_f32_e32 v50, v50, v51
	ds_bpermute_b32 v51, v104, v50
	s_waitcnt lgkmcnt(0)
	v_max3_f32 v163, v55, v50, v51
	v_sub_f32_e32 v42, v42, v163
	v_exp_f32_e32 v59, v42
	v_sub_f32_e32 v42, v43, v163
	v_exp_f32_e32 v64, v42
	v_sub_f32_e32 v42, v44, v163
	v_exp_f32_e32 v65, v42
	v_sub_f32_e32 v42, v45, v163
	v_exp_f32_e32 v160, v42
	v_sub_f32_e32 v42, v46, v163
	v_exp_f32_e32 v161, v42
	v_sub_f32_e32 v42, v47, v163
	v_exp_f32_e32 v162, v42
	v_sub_f32_e32 v42, v48, v163
	v_fma_f32 v50, v54, s2, -v163
	v_exp_f32_e32 v168, v42
	v_sub_f32_e32 v42, v49, v163
	v_exp_f32_e32 v169, v42
	v_exp_f32_e32 v58, v50
	v_cvt_pk_bf16_f32 v54, v59, v64
	v_cvt_pk_bf16_f32 v55, v65, v160
	v_cvt_pk_bf16_f32 v56, v161, v162
	v_cvt_pk_bf16_f32 v57, v168, v169
	s_nop 0
	v_cmp_neq_f32_e32 vcc, 1.0, v58
	s_cmp_eq_u64 vcc, 0
	s_cselect_b64 s[2:3], -1, 0
	v_mul_f32_e32 v46, 0, v58
	v_cndmask_b32_e64 v60, v46, 0, s[2:3]
	v_mov_b32_e32 v61, v60
	v_mov_b32_e32 v62, v60
	v_mov_b32_e32 v63, v60
	s_nop 0
	s_waitcnt lgkmcnt(0)
	v_mfma_f32_16x16x32_bf16 v[46:49], v[186:189], v[54:57], v[60:63]
	s_nop 0
	s_waitcnt lgkmcnt(0)
	v_mfma_f32_16x16x32_bf16 v[50:53], v[190:193], v[54:57], v[60:63]
	s_nop 0
	s_waitcnt lgkmcnt(0)
	v_mfma_f32_16x16x32_bf16 v[42:45], v[194:197], v[54:57], v[60:63]
	s_nop 2
	v_mul_f32_e64 v60, v58, 0
	v_mul_f32_e64 v61, v58, 0
	v_add_f32_e32 v59, 0, v59
	v_add_f32_e32 v59, v64, v59
	v_add_f32_e32 v59, v65, v59
	v_cndmask_b32_e64 v61, v61, 0, s[2:3]
	v_cndmask_b32_e64 v60, v60, 0, s[2:3]
	v_add_f32_e32 v59, v160, v59
	v_mov_b32_e32 v62, v60
	v_mov_b32_e32 v63, v61
	v_add_f32_e32 v59, v161, v59
	v_add_f32_e32 v59, v162, v59
	v_mfma_f32_16x16x32_bf16 v[54:57], v[198:201], v[54:57], v[60:63]
	v_add_f32_e32 v59, v168, v59
	v_add_f32_e32 v162, v169, v59
	v_fmac_f32_e32 v162, v101, v58
	v_mov_b32_e32 v160, v152
	v_mov_b32_e32 v161, v151
